# attention: s_setprio 1 around the QK and PV MFMA clusters
# baseline (speedup 1.0000x reference)
; #define MFMA16(a, b, c) __builtin_amdgcn_mfma_f32_16x16x32_bf16((a), (b), (c), 0, 0, 0)
;     ...
;             if (kt * 64 < q1w) {
;             f32x4 as[4][2];
; #pragma unroll
;             for (int kb = 0; kb < 4; ++kb)
; #pragma unroll
;                 for (int qb = 0; qb < 2; ++qb) as[kb][qb] = (f32x4){0.f, 0.f, 0.f, 0.f};
; #pragma unroll
;             for (int ds = 0; ds < 6; ++ds) {
;                 const int ch = 4 * ds + qq;
; #pragma unroll
;                 for (int kb = 0; kb < 4; ++kb) {
;                     const int krow = krow0 + 32 * (kb >> 1) + 4 * (kb & 1), key = kkey;
;                     const bf16x8 kf = *(const bf16x8*)(sb + krow * 384 + (((ch & 24) | ((ch ^ key) & 7)) << 4));
; #pragma unroll
;                     for (int qb = 0; qb < 2; ++qb) as[kb][qb] = MFMA16(kf, qf[ds][qb], as[kb][qb]);
;                 }
;             }
;             const bool need_mask = (kt >= 4 * qt) || (TMAX[((gtb) >> 6) + kt] > tminq);
.LBB0_931:
	s_add_u32 s98, s22, s90
	s_addc_u32 s99, s23, s91
	global_load_dword v251, v177, s[98:99]
	s_add_i32 s88, s0, 1
	s_bitcmp1_b32 s88, 0
	s_cselect_b32 s1, 0xa000, 0
	s_add_i32 s19, s1, 16
	v_readfirstlane_b32 s100, v186
	v_readfirstlane_b32 s101, v187
	v_cmp_lt_i32_e32 vcc, s92, v222
	s_add_i32 s100, s100, s19
	s_add_i32 s101, s101, s19
	s_and_saveexec_b64 s[26:27], vcc
	s_cbranch_execz .Lattn_skip_dma
	s_bitcmp1_b32 s0, 0
	s_cselect_b32 s1, 0xa000, 0
	s_add_i32 s93, s1, 16
	v_add3_u32 v148, s93, v198, v199
	v_add3_u32 v152, s93, v200, v199
	ds_read_b128 v[144:147], v148
	ds_read_b128 v[236:239], v148 offset:1536
	ds_read_b128 v[240:243], v148 offset:12288
	ds_read_b128 v[244:247], v148 offset:13824
	s_cmp_ge_u32 s0, s35
	s_cselect_b64 s[0:1], -1, 0
	s_and_b64 vcc, exec, s[0:1]
	v_add3_u32 v248, s93, v188, v201
	v_add3_u32 v250, s93, v188, v202
	s_waitcnt lgkmcnt(3)
	s_setprio 1
	v_mfma_f32_16x16x32_bf16 v[128:131], v[144:147], v[104:107], 0
	v_mfma_f32_16x16x32_bf16 v[116:119], v[144:147], v[108:111], 0
	s_mov_b32 m0, s100
	ds_read_b128 v[144:147], v152
	global_load_lds_dwordx4 v235, s[22:23]
	s_waitcnt lgkmcnt(3)
	v_mfma_f32_16x16x32_bf16 v[124:127], v[236:239], v[104:107], 0
	v_mfma_f32_16x16x32_bf16 v[112:115], v[236:239], v[108:111], 0
	s_add_i32 m0, s100, 0x400
	ds_read_b128 v[236:239], v152 offset:1536
	global_load_lds_dwordx4 v234, s[22:23]
	s_waitcnt lgkmcnt(3)
	v_mfma_f32_16x16x32_bf16 v[132:135], v[240:243], v[104:107], 0
	v_mfma_f32_16x16x32_bf16 v[120:123], v[240:243], v[108:111], 0
	s_add_i32 m0, s100, 0x800
	ds_read_b128 v[240:243], v152 offset:12288
	global_load_lds_dwordx4 v233, s[22:23]
	s_waitcnt lgkmcnt(3)
	v_mfma_f32_16x16x32_bf16 v[140:143], v[244:247], v[104:107], 0
	v_mfma_f32_16x16x32_bf16 v[136:139], v[244:247], v[108:111], 0
	s_add_i32 m0, s101, 0x6000
	ds_read_b128 v[244:247], v152 offset:13824
	global_load_lds_dwordx4 v232, s[22:23]
	s_waitcnt lgkmcnt(3)
	v_mfma_f32_16x16x32_bf16 v[128:131], v[144:147], v[96:99], v[128:131]
	v_mfma_f32_16x16x32_bf16 v[116:119], v[144:147], v[100:103], v[116:119]
	s_add_i32 m0, s101, 0x6400
	ds_read_b128 v[144:147], v148 offset:128
	global_load_lds_dwordx4 v231, s[22:23]
	s_waitcnt lgkmcnt(3)
	v_mfma_f32_16x16x32_bf16 v[124:127], v[236:239], v[96:99], v[124:127]
	v_mfma_f32_16x16x32_bf16 v[112:115], v[236:239], v[100:103], v[112:115]
	ds_read_b128 v[236:239], v148 offset:1664
	s_waitcnt lgkmcnt(3)
	v_mfma_f32_16x16x32_bf16 v[132:135], v[240:243], v[96:99], v[132:135]
	v_mfma_f32_16x16x32_bf16 v[120:123], v[240:243], v[100:103], v[120:123]
	ds_read_b128 v[240:243], v148 offset:12416
	s_waitcnt lgkmcnt(3)
	v_mfma_f32_16x16x32_bf16 v[140:143], v[244:247], v[96:99], v[140:143]
	v_mfma_f32_16x16x32_bf16 v[136:139], v[244:247], v[100:103], v[136:139]
	ds_read_b128 v[244:247], v148 offset:13952
	s_waitcnt lgkmcnt(3)
	v_mfma_f32_16x16x32_bf16 v[128:131], v[144:147], v[88:91], v[128:131]
	v_mfma_f32_16x16x32_bf16 v[116:119], v[144:147], v[92:95], v[116:119]
	ds_read_b128 v[144:147], v152 offset:128
	s_waitcnt lgkmcnt(3)
	v_mfma_f32_16x16x32_bf16 v[124:127], v[236:239], v[88:91], v[124:127]
	v_mfma_f32_16x16x32_bf16 v[112:115], v[236:239], v[92:95], v[112:115]
	ds_read_b128 v[236:239], v152 offset:1664
	s_waitcnt lgkmcnt(3)
	v_mfma_f32_16x16x32_bf16 v[132:135], v[240:243], v[88:91], v[132:135]
	v_mfma_f32_16x16x32_bf16 v[120:123], v[240:243], v[92:95], v[120:123]
	ds_read_b128 v[240:243], v152 offset:12416
	s_waitcnt lgkmcnt(3)
	v_mfma_f32_16x16x32_bf16 v[140:143], v[244:247], v[88:91], v[140:143]
	v_mfma_f32_16x16x32_bf16 v[136:139], v[244:247], v[92:95], v[136:139]
	ds_read_b128 v[244:247], v152 offset:13952
	s_waitcnt lgkmcnt(3)
	v_mfma_f32_16x16x32_bf16 v[128:131], v[144:147], v[80:83], v[128:131]
	v_mfma_f32_16x16x32_bf16 v[116:119], v[144:147], v[84:87], v[116:119]
	ds_read_b128 v[144:147], v148 offset:256
	s_waitcnt lgkmcnt(3)
	v_mfma_f32_16x16x32_bf16 v[124:127], v[236:239], v[80:83], v[124:127]
	v_mfma_f32_16x16x32_bf16 v[112:115], v[236:239], v[84:87], v[112:115]
	ds_read_b128 v[236:239], v148 offset:1792
	s_waitcnt lgkmcnt(3)
	v_mfma_f32_16x16x32_bf16 v[132:135], v[240:243], v[80:83], v[132:135]
	v_mfma_f32_16x16x32_bf16 v[120:123], v[240:243], v[84:87], v[120:123]
	ds_read_b128 v[240:243], v148 offset:12544
	s_waitcnt lgkmcnt(3)
	v_mfma_f32_16x16x32_bf16 v[140:143], v[244:247], v[80:83], v[140:143]
	v_mfma_f32_16x16x32_bf16 v[136:139], v[244:247], v[84:87], v[136:139]
	ds_read_b128 v[244:247], v148 offset:14080
	s_waitcnt lgkmcnt(3)
	v_mfma_f32_16x16x32_bf16 v[128:131], v[144:147], v[72:75], v[128:131]
	v_mfma_f32_16x16x32_bf16 v[116:119], v[144:147], v[76:79], v[116:119]
	ds_read_b128 v[144:147], v152 offset:256
	s_waitcnt lgkmcnt(3)
	v_mfma_f32_16x16x32_bf16 v[124:127], v[236:239], v[72:75], v[124:127]
	v_mfma_f32_16x16x32_bf16 v[112:115], v[236:239], v[76:79], v[112:115]
	ds_read_b128 v[236:239], v152 offset:1792
	s_waitcnt lgkmcnt(3)
	v_mfma_f32_16x16x32_bf16 v[132:135], v[240:243], v[72:75], v[132:135]
	v_mfma_f32_16x16x32_bf16 v[120:123], v[240:243], v[76:79], v[120:123]
	ds_read_b128 v[240:243], v152 offset:12544
	s_waitcnt lgkmcnt(3)
	v_mfma_f32_16x16x32_bf16 v[140:143], v[244:247], v[72:75], v[140:143]
	v_mfma_f32_16x16x32_bf16 v[136:139], v[244:247], v[76:79], v[136:139]
	ds_read_b128 v[244:247], v152 offset:14080
	s_waitcnt lgkmcnt(3)
	v_mfma_f32_16x16x32_bf16 v[128:131], v[144:147], v[64:67], v[128:131]
	v_mfma_f32_16x16x32_bf16 v[116:119], v[144:147], v[68:71], v[116:119]
	s_waitcnt lgkmcnt(2)
	v_mfma_f32_16x16x32_bf16 v[124:127], v[236:239], v[64:67], v[124:127]
	v_mfma_f32_16x16x32_bf16 v[112:115], v[236:239], v[68:71], v[112:115]
	ds_read_b128 v[236:239], v248 offset:24576
	s_waitcnt lgkmcnt(2)
	v_mfma_f32_16x16x32_bf16 v[132:135], v[240:243], v[64:67], v[132:135]
	v_mfma_f32_16x16x32_bf16 v[120:123], v[240:243], v[68:71], v[120:123]
	ds_read_b128 v[240:243], v248 offset:26624
	s_waitcnt lgkmcnt(2)
	v_mfma_f32_16x16x32_bf16 v[140:143], v[244:247], v[64:67], v[140:143]
	v_mfma_f32_16x16x32_bf16 v[136:139], v[244:247], v[68:71], v[136:139]
	ds_read_b128 v[244:247], v248 offset:28672
	s_setprio 0
	s_cbranch_vccnz .LBB0_934
	s_waitcnt vmcnt(5)
	v_cmp_gt_i32_e64 s[0:1], v251, v223

; #define MFMA16(a, b, c) __builtin_amdgcn_mfma_f32_16x16x32_bf16((a), (b), (c), 0, 0, 0)
; DI unsigned pk2(float lo, float hi) { f32x2 v = {lo, hi}; return __builtin_bit_cast(unsigned, __builtin_convertvector(v, bf16x2_t)); }
; DI float fexp2(float x) { return __builtin_amdgcn_exp2f(x); }
;     ...
;                 float ps = 0.f;
; #pragma unroll
;                 for (int kb = 0; kb < 4; ++kb)
; #pragma unroll
;                     for (int rr = 0; rr < 4; ++rr) { const float pv = fexp2(as[kb][qb][rr] - mnew); as[kb][qb][rr] = pv; ps += pv; }
;                 lsum[qb] = lsum[qb] * alpha[qb] + ps;
;             }
;             if (__builtin_amdgcn_ballot_w64(alpha[0] != 1.f || alpha[1] != 1.f) != 0ull) {
; #pragma unroll
;                 for (int d = 0; d < 8; ++d)
; #pragma unroll
;                     for (int qb = 0; qb < 2; ++qb) ao[d][qb] = ao[d][qb] * alpha[qb];
;             }
;             bf16x8 pf[2][2];
; #pragma unroll
;             for (int k2 = 0; k2 < 2; ++k2)
; #pragma unroll
;                 for (int qb = 0; qb < 2; ++qb) {
;                     u32x4 pkd;
;                     pkd.x = pk2(as[2 * k2][qb][0], as[2 * k2][qb][1]); pkd.y = pk2(as[2 * k2][qb][2], as[2 * k2][qb][3]);
;                     pkd.z = pk2(as[2 * k2 + 1][qb][0], as[2 * k2 + 1][qb][1]); pkd.w = pk2(as[2 * k2 + 1][qb][2], as[2 * k2 + 1][qb][3]);
;                     pf[k2][qb] = __builtin_bit_cast(bf16x8, pkd);
;                 }
; #pragma unroll
;             for (int k2 = 0; k2 < 2; ++k2) {
;                 const int ph = ((4 * k2 + qq) ^ vkey) << 4;
; #pragma unroll
;                 for (int d = 0; d < 8; ++d) {
;                     const bf16x8 vf = *(const bf16x8*)(sb + AT_KB + (d * 16 + r16) * 128 + ph);
; #pragma unroll
;                     for (int qb = 0; qb < 2; ++qb) ao[d][qb] = MFMA16(vf, pf[k2][qb], ao[d][qb]);
;                 }
;             }
.LBB0_938:
	v_sub_f32_e32 v129, v129, v146
	v_exp_f32_e32 v148, v129
	v_sub_f32_e32 v129, v130, v146
	v_sub_f32_e32 v128, v128, v146
	v_exp_f32_e32 v130, v129
	v_sub_f32_e32 v129, v131, v146
	v_sub_f32_e32 v124, v124, v146
	v_sub_f32_e32 v116, v116, v147
	v_sub_f32_e32 v112, v112, v147
	v_exp_f32_e32 v128, v128
	v_exp_f32_e32 v150, v129
	v_exp_f32_e32 v152, v124
	v_sub_f32_e32 v124, v125, v146
	v_exp_f32_e32 v129, v116
	v_sub_f32_e32 v116, v117, v147
	v_exp_f32_e32 v153, v112
	v_sub_f32_e32 v112, v113, v147
	v_exp_f32_e32 v154, v124
	v_sub_f32_e32 v124, v126, v146
	v_exp_f32_e32 v149, v116
	v_sub_f32_e32 v116, v118, v147
	v_exp_f32_e32 v155, v112
	v_sub_f32_e32 v112, v114, v147
	v_exp_f32_e32 v126, v124
	v_sub_f32_e32 v124, v127, v146
	v_exp_f32_e32 v131, v116
	v_sub_f32_e32 v116, v119, v147
	v_exp_f32_e32 v127, v112
	v_sub_f32_e32 v112, v115, v147
	v_exp_f32_e32 v156, v124
	v_sub_f32_e32 v124, v132, v146
	v_exp_f32_e32 v151, v116
	v_exp_f32_e32 v157, v112
	v_sub_f32_e32 v112, v120, v147
	v_exp_f32_e32 v132, v124
	v_sub_f32_e32 v124, v133, v146
	v_exp_f32_e32 v133, v112
	v_pk_add_f32 v[112:113], v[128:129], 0 op_sel_hi:[1,0]
	v_sub_f32_e32 v114, v121, v147
	v_pk_add_f32 v[112:113], v[148:149], v[112:113]
	v_exp_f32_e32 v158, v124
	v_pk_add_f32 v[112:113], v[130:131], v[112:113]
	v_sub_f32_e32 v124, v134, v146
	v_pk_add_f32 v[112:113], v[150:151], v[112:113]
	v_exp_f32_e32 v159, v114
	v_pk_add_f32 v[112:113], v[152:153], v[112:113]
	v_sub_f32_e32 v114, v122, v147
	v_pk_add_f32 v[112:113], v[154:155], v[112:113]
	v_exp_f32_e32 v134, v124
	v_sub_f32_e32 v124, v135, v146
	v_pk_add_f32 v[112:113], v[126:127], v[112:113]
	v_exp_f32_e32 v135, v114
	v_sub_f32_e32 v114, v123, v147
	v_exp_f32_e32 v208, v124
	v_sub_f32_e32 v124, v140, v146
	v_pk_add_f32 v[112:113], v[156:157], v[112:113]
	v_exp_f32_e32 v209, v114
	v_sub_f32_e32 v114, v136, v147
	v_exp_f32_e32 v140, v124
	v_sub_f32_e32 v124, v141, v146
	v_pk_add_f32 v[112:113], v[132:133], v[112:113]
	v_exp_f32_e32 v141, v114
	v_sub_f32_e32 v114, v137, v147
	v_exp_f32_e32 v214, v124
	v_sub_f32_e32 v124, v142, v146
	v_exp_f32_e32 v215, v114
	v_sub_f32_e32 v114, v138, v147
	v_pk_add_f32 v[112:113], v[158:159], v[112:113]
	v_exp_f32_e32 v142, v124
	v_sub_f32_e32 v124, v143, v146
	v_exp_f32_e32 v143, v114
	v_sub_f32_e32 v114, v139, v147
	v_pk_add_f32 v[112:113], v[134:135], v[112:113]
	v_exp_f32_e32 v220, v124
	v_exp_f32_e32 v221, v114
	v_pk_add_f32 v[112:113], v[208:209], v[112:113]
	v_cvt_pk_bf16_f32 v116, v132, v158
	v_pk_add_f32 v[112:113], v[140:141], v[112:113]
	v_pk_add_f32 v[112:113], v[214:215], v[112:113]
	v_cvt_pk_bf16_f32 v120, v128, v148
	v_pk_add_f32 v[112:113], v[142:143], v[112:113]
	v_cvt_pk_bf16_f32 v121, v130, v150
	v_pk_add_f32 v[112:113], v[220:221], v[112:113]
	v_cvt_pk_bf16_f32 v124, v129, v149
	v_pk_fma_f32 v[172:173], v[172:173], v[144:145], v[112:113]
	v_cvt_pk_bf16_f32 v112, v133, v159
	v_cvt_pk_bf16_f32 v125, v131, v151
	ds_read_b128 v[128:131], v248 offset:30720
	v_cvt_pk_bf16_f32 v122, v152, v154
	v_cvt_pk_bf16_f32 v123, v126, v156
	v_cvt_pk_bf16_f32 v126, v153, v155
	v_cvt_pk_bf16_f32 v127, v127, v157
	s_waitcnt lgkmcnt(3)
	s_setprio 1
	v_mfma_f32_16x16x32_bf16 v[56:59], v[236:239], v[120:123], v[56:59]
	v_cvt_pk_bf16_f32 v117, v134, v208
	v_cvt_pk_bf16_f32 v118, v140, v214
	v_cvt_pk_bf16_f32 v119, v142, v220
	v_mfma_f32_16x16x32_bf16 v[44:47], v[236:239], v[124:127], v[44:47]
	ds_read_b128 v[236:239], v248 offset:32768
	v_cvt_pk_bf16_f32 v113, v135, v209
	v_cvt_pk_bf16_f32 v114, v141, v215
	s_waitcnt lgkmcnt(3)
	v_mfma_f32_16x16x32_bf16 v[60:63], v[240:243], v[120:123], v[60:63]
	v_cvt_pk_bf16_f32 v115, v143, v221
	v_mov_b32_e32 v224, v147
	v_mov_b32_e32 v225, v146
	v_mfma_f32_16x16x32_bf16 v[48:51], v[240:243], v[124:127], v[48:51]
	ds_read_b128 v[240:243], v248 offset:34816
	s_waitcnt lgkmcnt(3)
	v_mfma_f32_16x16x32_bf16 v[52:55], v[244:247], v[120:123], v[52:55]
	v_mfma_f32_16x16x32_bf16 v[36:39], v[244:247], v[124:127], v[36:39]
	ds_read_b128 v[244:247], v248 offset:36864
	s_waitcnt lgkmcnt(3)
	v_mfma_f32_16x16x32_bf16 v[40:43], v[128:131], v[120:123], v[40:43]
	v_mfma_f32_16x16x32_bf16 v[28:31], v[128:131], v[124:127], v[28:31]
	ds_read_b128 v[128:131], v248 offset:38912
	s_waitcnt lgkmcnt(3)
	v_mfma_f32_16x16x32_bf16 v[32:35], v[236:239], v[120:123], v[32:35]
	v_mfma_f32_16x16x32_bf16 v[16:19], v[236:239], v[124:127], v[16:19]
	ds_read_b128 v[236:239], v250 offset:24576
	s_waitcnt lgkmcnt(3)
	v_mfma_f32_16x16x32_bf16 v[20:23], v[240:243], v[120:123], v[20:23]
	v_mfma_f32_16x16x32_bf16 v[0:3], v[240:243], v[124:127], v[0:3]
	ds_read_b128 v[240:243], v250 offset:26624
	s_waitcnt lgkmcnt(3)
	v_mfma_f32_16x16x32_bf16 v[8:11], v[244:247], v[120:123], v[8:11]
	v_mfma_f32_16x16x32_bf16 v[4:7], v[244:247], v[124:127], v[4:7]
	ds_read_b128 v[244:247], v250 offset:28672
	s_waitcnt lgkmcnt(3)
	v_mfma_f32_16x16x32_bf16 v[24:27], v[128:131], v[120:123], v[24:27]
	v_mfma_f32_16x16x32_bf16 v[12:15], v[128:131], v[124:127], v[12:15]
	ds_read_b128 v[128:131], v250 offset:30720
	s_waitcnt lgkmcnt(3)
	v_mfma_f32_16x16x32_bf16 v[56:59], v[236:239], v[116:119], v[56:59]
	v_mfma_f32_16x16x32_bf16 v[44:47], v[236:239], v[112:115], v[44:47]
	ds_read_b128 v[236:239], v250 offset:32768
	s_waitcnt lgkmcnt(3)
	v_mfma_f32_16x16x32_bf16 v[60:63], v[240:243], v[116:119], v[60:63]
	v_mfma_f32_16x16x32_bf16 v[48:51], v[240:243], v[112:115], v[48:51]
	ds_read_b128 v[240:243], v250 offset:34816
	s_waitcnt lgkmcnt(3)
	v_mfma_f32_16x16x32_bf16 v[52:55], v[244:247], v[116:119], v[52:55]
	v_mfma_f32_16x16x32_bf16 v[36:39], v[244:247], v[112:115], v[36:39]
	ds_read_b128 v[244:247], v250 offset:36864
	s_waitcnt lgkmcnt(3)
	v_mfma_f32_16x16x32_bf16 v[40:43], v[128:131], v[116:119], v[40:43]
	v_mfma_f32_16x16x32_bf16 v[28:31], v[128:131], v[112:115], v[28:31]
	ds_read_b128 v[128:131], v250 offset:38912
	s_waitcnt lgkmcnt(3)
	v_mfma_f32_16x16x32_bf16 v[32:35], v[236:239], v[116:119], v[32:35]
	v_mfma_f32_16x16x32_bf16 v[16:19], v[236:239], v[112:115], v[16:19]
	s_waitcnt lgkmcnt(2)
	v_mfma_f32_16x16x32_bf16 v[20:23], v[240:243], v[116:119], v[20:23]
	v_mfma_f32_16x16x32_bf16 v[0:3], v[240:243], v[112:115], v[0:3]
	s_waitcnt lgkmcnt(1)
	v_mfma_f32_16x16x32_bf16 v[8:11], v[244:247], v[116:119], v[8:11]
	v_mfma_f32_16x16x32_bf16 v[4:7], v[244:247], v[112:115], v[4:7]
	s_waitcnt lgkmcnt(0)
	v_mfma_f32_16x16x32_bf16 v[24:27], v[128:131], v[116:119], v[24:27]
	v_mfma_f32_16x16x32_bf16 v[12:15], v[128:131], v[112:115], v[12:15]
	s_setprio 0
